# mLSTM: decay-table reads hoisted out of the masked score blocks, normaliser-finish reads batched (bit-identical)
# speedup vs baseline: 1.0375x; 1.0066x over previous
; #define LAS __attribute__((address_space(3)))
; __device__ __forceinline__ unsigned pk2(float lo, float hi) { f32x2_t v = {lo, hi}; bf16x2_t b = __builtin_convertvector(v, bf16x2_t); return __builtin_bit_cast(unsigned, b); }
; __device__ __forceinline__ float siluf_(float x) { return x * __builtin_amdgcn_rcpf(1.0f + __expf(-x)); }
; __device__ __forceinline__ void mlstm_unit(int unit, int l, const bf16_t* proj, const float* gif, const float* conv_w, const float* conv_b, bf16_t* mpart, float* dpart, int gplanes, LAS unsigned char* lds) {
;     ...
;         const LAS float* bcum = tabs + (c & 1) * 192; const LAS float* ig = bcum + 64; const LAS float* wsc = bcum + 128;
;         const float Gc = bcum[63];
;         {
;             float cwr[5][8];
; #pragma unroll
;             for (int tap = 0; tap < 5; ++tap) { const f32x4 a = *(const LAS f32x4*)(CWL + tap * 128 + dgi * 8), c2 = *(const LAS f32x4*)(CWL + tap * 128 + dgi * 8 + 4);
;                 cwr[tap][0] = a[0]; cwr[tap][1] = a[1]; cwr[tap][2] = a[2]; cwr[tap][3] = a[3]; cwr[tap][4] = c2[0]; cwr[tap][5] = c2[1]; cwr[tap][6] = c2[2]; cwr[tap][7] = c2[3]; }
;             LAS bf16_t* dst = ((dgi >> 3) ? KK : Q) + (run * 2) * 72 + (dgi & 7) * 8;
; #pragma unroll
;             for (int i = 0; i < 2; ++i) {
;                 float a[8];
; #pragma unroll
;                 for (int j = 0; j < 8; ++j) a[j] = cwr[4][j];
; #pragma unroll
;                 for (int tap = 0; tap < 4; ++tap) { float xf[8]; unpack8(pf[i + tap], xf);
; #pragma unroll
;                     for (int j = 0; j < 8; ++j) a[j] += cwr[tap][j] * xf[j]; }
; #pragma unroll
;                 for (int j = 0; j < 8; ++j) a[j] = siluf_(a[j]);
;                 u32x4 o; o.x = pk2(a[0], a[1]); o.y = pk2(a[2], a[3]); o.z = pk2(a[4], a[5]); o.w = pk2(a[6], a[7]);
;                 *(LAS u32x4*)(dst + i * 72) = o;
;             }
.LBB0_423:
	s_bitcmp1_b32 s36, 0
	s_cselect_b32 s7, 0x300, 0
	s_add_i32 s7, s7, 0
	s_add_i32 s7, s7, 0x20e00
	v_mov_b32_e32 v1, s7
	ds_read_b32 v1, v1 offset:252
	ds_read_b128 v[96:99], v113
	ds_read_b128 v[72:75], v113 offset:16
	ds_read_b128 v[100:103], v113 offset:512
	ds_read_b128 v[76:79], v113 offset:528
	ds_read_b128 v[104:107], v113 offset:1024
	ds_read_b128 v[80:83], v113 offset:1040
	ds_read_b128 v[92:95], v113 offset:1536
	ds_read_b128 v[84:87], v113 offset:1552
	ds_read_b128 v[108:111], v113 offset:2048
	ds_read_b128 v[88:91], v113 offset:2064
	v_lshlrev_b32_e32 v144, 16, v4
	v_and_b32_e32 v145, 0xffff0000, v4
	v_lshlrev_b32_e32 v182, 16, v9
	s_waitcnt lgkmcnt(1)
	v_pk_fma_f32 v[146:147], v[96:97], v[144:145], v[108:109]
	v_lshlrev_b32_e32 v144, 16, v8
	v_and_b32_e32 v145, 0xffff0000, v8
	v_pk_fma_f32 v[148:149], v[100:101], v[144:145], v[146:147]
	v_lshlrev_b32_e32 v146, 16, v12
	v_and_b32_e32 v147, 0xffff0000, v12
	v_pk_fma_f32 v[178:179], v[104:105], v[146:147], v[148:149]
	v_lshlrev_b32_e32 v148, 16, v16
	v_and_b32_e32 v149, 0xffff0000, v16
	v_pk_fma_f32 v[178:179], v[92:93], v[148:149], v[178:179]
	v_and_b32_e32 v183, 0xffff0000, v9
	v_mul_f32_e32 v180, 0xbfb8aa3b, v178
	v_mul_f32_e32 v181, 0xbfb8aa3b, v179
	v_exp_f32_e32 v180, v180
	v_exp_f32_e32 v181, v181
	v_lshlrev_b32_e32 v184, 16, v13
	v_and_b32_e32 v185, 0xffff0000, v13
	v_add_f32_e32 v180, 1.0, v180
	v_add_f32_e32 v181, 1.0, v181
	v_rcp_f32_e32 v180, v180
	v_rcp_f32_e32 v181, v181
	v_lshlrev_b32_e32 v186, 16, v17
	v_and_b32_e32 v187, 0xffff0000, v17
	v_lshlrev_b32_e32 v190, 16, v10
	v_pk_mul_f32 v[178:179], v[178:179], v[180:181]
	v_lshlrev_b32_e32 v180, 16, v5
	v_and_b32_e32 v181, 0xffff0000, v5
	v_pk_fma_f32 v[180:181], v[98:99], v[180:181], v[110:111]
	v_and_b32_e32 v191, 0xffff0000, v10
	v_pk_fma_f32 v[180:181], v[102:103], v[182:183], v[180:181]
	v_lshlrev_b32_e32 v192, 16, v14
	v_pk_fma_f32 v[180:181], v[106:107], v[184:185], v[180:181]
	v_and_b32_e32 v193, 0xffff0000, v14
	v_pk_fma_f32 v[180:181], v[94:95], v[186:187], v[180:181]
	v_pk_fma_f32 v[96:97], v[96:97], v[144:145], v[108:109]
	v_mul_f32_e32 v188, 0xbfb8aa3b, v180
	v_mul_f32_e32 v189, 0xbfb8aa3b, v181
	v_exp_f32_e32 v188, v188
	v_exp_f32_e32 v189, v189
	v_lshlrev_b32_e32 v194, 16, v18
	v_and_b32_e32 v195, 0xffff0000, v18
	v_add_f32_e32 v188, 1.0, v188
	v_add_f32_e32 v189, 1.0, v189
	v_rcp_f32_e32 v188, v188
	v_rcp_f32_e32 v189, v189
	v_pk_fma_f32 v[96:97], v[100:101], v[146:147], v[96:97]
	v_lshlrev_b32_e32 v100, 16, v20
	v_pk_fma_f32 v[96:97], v[104:105], v[148:149], v[96:97]
	v_pk_mul_f32 v[180:181], v[180:181], v[188:189]
	v_lshlrev_b32_e32 v188, 16, v6
	v_and_b32_e32 v189, 0xffff0000, v6
	s_waitcnt lgkmcnt(0)
	v_pk_fma_f32 v[188:189], v[72:73], v[188:189], v[88:89]
	v_pk_fma_f32 v[72:73], v[72:73], v[190:191], v[88:89]
	v_pk_fma_f32 v[188:189], v[76:77], v[190:191], v[188:189]
	v_pk_fma_f32 v[72:73], v[76:77], v[192:193], v[72:73]
	v_pk_fma_f32 v[188:189], v[80:81], v[192:193], v[188:189]
	v_and_b32_e32 v101, 0xffff0000, v20
	v_pk_fma_f32 v[188:189], v[84:85], v[194:195], v[188:189]
	v_pk_fma_f32 v[72:73], v[80:81], v[194:195], v[72:73]
	v_lshlrev_b32_e32 v76, 16, v22
	v_and_b32_e32 v77, 0xffff0000, v22
	v_mul_f32_e32 v196, 0xbfb8aa3b, v188
	v_mul_f32_e32 v197, 0xbfb8aa3b, v189
	v_pk_fma_f32 v[92:93], v[92:93], v[100:101], v[96:97]
	v_pk_fma_f32 v[72:73], v[84:85], v[76:77], v[72:73]
	v_exp_f32_e32 v196, v196
	v_exp_f32_e32 v197, v197
	v_mul_f32_e32 v96, 0xbfb8aa3b, v92
	v_mul_f32_e32 v97, 0xbfb8aa3b, v93
	v_mul_f32_e32 v76, 0xbfb8aa3b, v72
	v_mul_f32_e32 v77, 0xbfb8aa3b, v73
	v_exp_f32_e32 v96, v96
	v_exp_f32_e32 v97, v97
	v_exp_f32_e32 v76, v76
	v_exp_f32_e32 v77, v77
	v_add_f32_e32 v196, 1.0, v196
	v_add_f32_e32 v197, 1.0, v197
	v_rcp_f32_e32 v196, v196
	v_rcp_f32_e32 v197, v197
	v_add_f32_e32 v96, 1.0, v96
	v_add_f32_e32 v97, 1.0, v97
	v_add_f32_e32 v76, 1.0, v76
	v_add_f32_e32 v77, 1.0, v77
	v_rcp_f32_e32 v96, v96
	v_rcp_f32_e32 v97, v97
	v_rcp_f32_e32 v76, v76
	v_rcp_f32_e32 v77, v77
	v_pk_mul_f32 v[188:189], v[188:189], v[196:197]
	v_lshlrev_b32_e32 v196, 16, v7
	v_and_b32_e32 v197, 0xffff0000, v7
	v_lshlrev_b32_e32 v198, 16, v11
	v_and_b32_e32 v199, 0xffff0000, v11
	v_pk_fma_f32 v[196:197], v[74:75], v[196:197], v[90:91]
	v_lshlrev_b32_e32 v200, 16, v15
	v_and_b32_e32 v201, 0xffff0000, v15
	v_pk_mul_f32 v[92:93], v[92:93], v[96:97]
	v_pk_fma_f32 v[96:97], v[98:99], v[182:183], v[110:111]
	v_pk_mul_f32 v[76:77], v[72:73], v[76:77]
	v_pk_fma_f32 v[72:73], v[74:75], v[198:199], v[90:91]
	v_pk_fma_f32 v[196:197], v[78:79], v[198:199], v[196:197]
	v_lshlrev_b32_e32 v206, 16, v19
	v_and_b32_e32 v207, 0xffff0000, v19
	v_pk_fma_f32 v[96:97], v[102:103], v[184:185], v[96:97]
	v_pk_fma_f32 v[72:73], v[78:79], v[200:201], v[72:73]
	v_pk_fma_f32 v[196:197], v[82:83], v[200:201], v[196:197]
	v_pk_fma_f32 v[96:97], v[106:107], v[186:187], v[96:97]
	v_lshlrev_b32_e32 v98, 16, v21
	v_and_b32_e32 v99, 0xffff0000, v21
	v_pk_fma_f32 v[72:73], v[82:83], v[206:207], v[72:73]
	v_lshlrev_b32_e32 v74, 16, v23
	v_and_b32_e32 v75, 0xffff0000, v23
	v_pk_fma_f32 v[196:197], v[86:87], v[206:207], v[196:197]
	v_pk_fma_f32 v[94:95], v[94:95], v[98:99], v[96:97]
	v_pk_fma_f32 v[72:73], v[86:87], v[74:75], v[72:73]
	v_mul_f32_e32 v208, 0xbfb8aa3b, v196
	v_mul_f32_e32 v209, 0xbfb8aa3b, v197
	v_mul_f32_e32 v96, 0xbfb8aa3b, v94
	v_mul_f32_e32 v97, 0xbfb8aa3b, v95
	v_mul_f32_e32 v74, 0xbfb8aa3b, v72
	v_mul_f32_e32 v75, 0xbfb8aa3b, v73
	v_exp_f32_e32 v208, v208
	v_exp_f32_e32 v209, v209
	v_exp_f32_e32 v96, v96
	v_exp_f32_e32 v97, v97
	v_exp_f32_e32 v74, v74
	v_exp_f32_e32 v75, v75
	v_add_f32_e32 v208, 1.0, v208
	v_add_f32_e32 v209, 1.0, v209
	v_add_f32_e32 v96, 1.0, v96
	v_add_f32_e32 v97, 1.0, v97
	v_add_f32_e32 v74, 1.0, v74
	v_add_f32_e32 v75, 1.0, v75
	v_rcp_f32_e32 v208, v208
	v_rcp_f32_e32 v209, v209
	v_rcp_f32_e32 v96, v96
	v_rcp_f32_e32 v97, v97
	v_rcp_f32_e32 v74, v74
	v_rcp_f32_e32 v75, v75
	s_cmp_lg_u32 s88, 0
	v_pk_mul_f32 v[196:197], v[196:197], v[208:209]
	v_pk_mul_f32 v[94:95], v[94:95], v[96:97]
	v_pk_mul_f32 v[78:79], v[72:73], v[74:75]
	s_cselect_b64 s[8:9], -1, 0
	v_cvt_pk_bf16_f32 v178, v178, v179
	v_cvt_pk_bf16_f32 v179, v180, v181
	v_cvt_pk_bf16_f32 v180, v188, v189
	v_cvt_pk_bf16_f32 v181, v196, v197
	v_cvt_pk_bf16_f32 v72, v92, v93
	v_cvt_pk_bf16_f32 v73, v94, v95
	v_cvt_pk_bf16_f32 v74, v76, v77
	v_cvt_pk_bf16_f32 v75, v78, v79
	s_and_b64 s[8:9], s[38:39], s[8:9]
	ds_write_b128 v150, v[178:181]
	ds_write_b128 v150, v[72:75] offset:144
	s_and_saveexec_b64 s[76:77], s[8:9]
	s_cbranch_execz .LBB0_425
; __device__ __forceinline__ void mlstm_unit(int unit, int l, const bf16_t* proj, const float* gif, const float* conv_w, const float* conv_b, bf16_t* mpart, float* dpart, int gplanes, LAS unsigned char* lds) {
;     ...
;             if (c > 0 && tid < 64) {
;                 float sn = 0.f;
; #pragma unroll
;                 for (int w8 = 0; w8 < 8; ++w8) sn += npart[w8 * 64 + tid];
;                 nvec[tid] = __expf(tabs[((c - 1) & 1) * 192 + 63]) * nvec[tid] + sn;
;             }
	ds_read2st64_b32 v[72:73], v152 offset1:1
	ds_read2st64_b32 v[74:75], v152 offset0:2 offset1:3
	ds_read2st64_b32 v[76:77], v152 offset0:4 offset1:5
	ds_read2st64_b32 v[78:79], v152 offset0:6 offset1:7
	s_andn2_b32 s8, 1, s36
	s_mulk_i32 s8, 0x300
	s_add_i32 s8, s8, 0
	s_add_i32 s8, s8, 0x20efc
	v_mov_b32_e32 v80, s8
	ds_read_b32 v80, v80
	ds_read_b32 v81, v153
	s_waitcnt lgkmcnt(2)
	v_add_f32_e32 v72, 0, v72
	v_add_f32_e32 v72, v72, v73
	v_add_f32_e32 v72, v72, v74
	v_add_f32_e32 v72, v72, v75
	v_add_f32_e32 v72, v72, v76
	v_add_f32_e32 v72, v72, v77
	v_add_f32_e32 v72, v72, v78
	v_add_f32_e32 v72, v72, v79
	s_waitcnt lgkmcnt(1)
	v_mul_f32_e32 v80, 0x3fb8aa3b, v80
	v_exp_f32_e32 v80, v80
	s_waitcnt lgkmcnt(0)
	v_fmac_f32_e32 v72, v81, v80
	ds_write_b32 v153, v72

; __device__ __forceinline__ unsigned f2bf(float f) { return pk2(f, 0.f) & 0xffffu; }
; __device__ __forceinline__ float sum16(float v) { v += __shfl_xor(v, 1); v += __shfl_xor(v, 2); v += __shfl_xor(v, 4); v += __shfl_xor(v, 8); return v; }
; #define MFMA16(a, b, c) __builtin_amdgcn_mfma_f32_16x16x32_bf16((a), (b), (c), 0, 0, 0)
; __device__ __forceinline__ void mlstm_unit(int unit, int l, const bf16_t* proj, const float* gif, const float* conv_w, const float* conv_b, bf16_t* mpart, float* dpart, int gplanes, LAS unsigned char* lds) {
;     ...
;             for (int ks = 0; ks < 2; ++ks) { const bf16x8 a = frag(Q, 72, mt, ks, lane); s0 = MFMA16(a, frag(KK, 72, nt0, ks, lane), s0); s1 = MFMA16(a, frag(KK, 72, nt0 + 1, ks, lane), s1); }
;             float rs[4];
; #pragma unroll
;             for (int j = 0; j < 4; ++j) {
;                 const int t = 16 * mt + 4 * g + j; const float bt = bcum[t];
;                 const int sa = 16 * nt0 + c16, sb = sa + 16;
;                 const float va = (sa <= t) ? s0[j] * __expf(bt - bcum[sa] + ig[sa]) * 0.0625f : 0.f;
;                 const float vb = (sb <= t) ? s1[j] * __expf(bt - bcum[sb] + ig[sb]) * 0.0625f : 0.f;
;                 AS[t * 72 + sa] = (bf16_t)f2bf(va); AS[t * 72 + sb] = (bf16_t)f2bf(vb);
;                 rs[j] = sum16(va + vb);
.LBB0_430:
	ds_read_b128 v[72:75], v120
	ds_read_b128 v[76:79], v154 offset:9216
	ds_read_b128 v[80:83], v154 offset:11520
	s_waitcnt lgkmcnt(1)
	v_mfma_f32_16x16x32_bf16 v[76:79], v[72:75], v[76:79], 0
	s_waitcnt lgkmcnt(0)
	v_mfma_f32_16x16x32_bf16 v[72:75], v[72:75], v[80:83], 0
	ds_read_b128 v[80:83], v120 offset:64
	ds_read_b128 v[84:87], v154 offset:9280
	s_waitcnt lgkmcnt(0)
	v_mfma_f32_16x16x32_bf16 v[76:79], v[80:83], v[84:87], v[76:79]
	ds_read_b128 v[84:87], v154 offset:11584
	s_waitcnt lgkmcnt(0)
	v_mfma_f32_16x16x32_bf16 v[72:75], v[80:83], v[84:87], v[72:75]
	v_lshl_add_u32 v82, v155, 2, s7
	ds_read_b32 v80, v82
	v_lshl_add_u32 v81, v121, 2, s7
	ds_read2st64_b32 v[92:93], v81 offset1:1
	ds_read2_b32 v[94:95], v81 offset0:16 offset1:80
	v_mov_b32_e32 v86, 0
	v_mov_b32_e32 v84, 0
	s_and_saveexec_b64 s[90:91], s[46:47]
	s_cbranch_execz .LBB0_432
	s_waitcnt lgkmcnt(0)
	v_sub_f32_e32 v83, v80, v92
	v_add_f32_e32 v83, v83, v93
	v_mul_f32_e32 v83, 0x3fb8aa3b, v83
	v_exp_f32_e32 v83, v83
	s_nop 0
	v_mul_f32_e32 v76, v76, v83
	v_mul_f32_e32 v84, 0x3d800000, v76
.LBB0_432:
	s_or_b64 exec, exec, s[90:91]
	v_mov_b32_e32 v85, 0
	s_and_saveexec_b64 s[90:91], s[48:49]
	s_cbranch_execz .LBB0_434
	s_waitcnt lgkmcnt(0)
	v_sub_f32_e32 v76, v80, v94
	v_add_f32_e32 v76, v76, v95
	v_mul_f32_e32 v76, 0x3fb8aa3b, v76
	v_exp_f32_e32 v76, v76
	s_nop 0
	v_mul_f32_e32 v72, v72, v76
	v_mul_f32_e32 v85, 0x3d800000, v72
.LBB0_434:
	s_or_b64 exec, exec, s[90:91]
	v_and_b32_e32 v104, 64, v217
	v_xor_b32_e32 v72, 1, v217
	v_add_u32_e32 v83, 64, v104
	v_cmp_lt_i32_e32 vcc, v72, v83
	v_xor_b32_e32 v76, 2, v217
	s_waitcnt lgkmcnt(0)
	v_xor_b32_e32 v80, 4, v217
	v_cndmask_b32_e32 v72, v217, v72, vcc
	v_cmp_lt_i32_e32 vcc, v76, v83
	v_xor_b32_e32 v87, 8, v217
	v_lshlrev_b32_e32 v72, 2, v72
	v_cndmask_b32_e32 v76, v217, v76, vcc
	v_cmp_lt_i32_e32 vcc, v80, v83
	v_lshlrev_b32_e32 v76, 2, v76
	ds_read_b32 v88, v82 offset:4
	v_cndmask_b32_e32 v80, v217, v80, vcc
	v_cmp_lt_i32_e32 vcc, v87, v83
	v_lshlrev_b32_e32 v80, 2, v80
	s_nop 0
	v_cndmask_b32_e32 v83, v217, v87, vcc
	v_cvt_pk_bf16_f32 v87, v84, s0
	v_add_f32_e32 v84, v84, v85
	ds_write_b16 v123, v87
	v_cvt_pk_bf16_f32 v87, v85, s0
	s_nop 1
	v_mov_b32_dpp v85, v84 quad_perm:[1,0,3,2] row_mask:0xf bank_mask:0xf
	v_lshlrev_b32_e32 v83, 2, v83
	ds_write_b16 v123, v87 offset:32
	s_waitcnt lgkmcnt(1)
	v_add_f32_e32 v84, v84, v85
	s_nop 1
	v_mov_b32_dpp v85, v84 quad_perm:[2,3,0,1] row_mask:0xf bank_mask:0xf
	s_waitcnt lgkmcnt(0)
	v_add_f32_e32 v84, v84, v85
	s_nop 1
	v_mov_b32_dpp v85, v84 row_half_mirror row_mask:0xf bank_mask:0xf
	s_waitcnt lgkmcnt(0)
	v_add_f32_e32 v84, v84, v85
	s_nop 1
	v_mov_b32_dpp v85, v84 row_mirror row_mask:0xf bank_mask:0xf
	s_and_saveexec_b64 s[90:91], s[50:51]
	s_cbranch_execz .LBB0_436
	s_waitcnt lgkmcnt(0)
	v_sub_f32_e32 v86, v88, v92
	v_add_f32_e32 v86, v86, v93
	v_mul_f32_e32 v86, 0x3fb8aa3b, v86
	v_exp_f32_e32 v86, v86
	s_nop 0
	v_mul_f32_e32 v77, v77, v86
	v_mul_f32_e32 v86, 0x3d800000, v77
.LBB0_436:
	s_or_b64 exec, exec, s[90:91]
	v_mov_b32_e32 v87, 0
	v_mov_b32_e32 v77, 0
	s_and_saveexec_b64 s[90:91], s[52:53]
	s_cbranch_execz .LBB0_438
	s_waitcnt lgkmcnt(0)
	v_sub_f32_e32 v77, v88, v94
	v_add_f32_e32 v77, v77, v95
	v_mul_f32_e32 v77, 0x3fb8aa3b, v77
	v_exp_f32_e32 v77, v77
	s_nop 0
	v_mul_f32_e32 v73, v73, v77
	v_mul_f32_e32 v77, 0x3d800000, v73
.LBB0_438:
	s_or_b64 exec, exec, s[90:91]
	v_cvt_pk_bf16_f32 v73, v86, s0
	ds_write_b16 v163, v73
	v_cvt_pk_bf16_f32 v73, v77, s0
	ds_write_b16 v163, v73 offset:32
	v_add_f32_e32 v73, v86, v77
	s_nop 1
	v_mov_b32_dpp v77, v73 quad_perm:[1,0,3,2] row_mask:0xf bank_mask:0xf
	ds_read_b32 v86, v82 offset:8
	s_waitcnt lgkmcnt(1)
	v_add_f32_e32 v73, v73, v77
	s_nop 1
	v_mov_b32_dpp v77, v73 quad_perm:[2,3,0,1] row_mask:0xf bank_mask:0xf
	s_waitcnt lgkmcnt(0)
	v_add_f32_e32 v73, v73, v77
	s_nop 1
	v_mov_b32_dpp v77, v73 row_half_mirror row_mask:0xf bank_mask:0xf
	s_waitcnt lgkmcnt(0)
	v_add_f32_e32 v73, v73, v77
	s_nop 1
	v_mov_b32_dpp v77, v73 row_mirror row_mask:0xf bank_mask:0xf
	s_and_saveexec_b64 s[90:91], s[54:55]
	s_cbranch_execz .LBB0_440
	s_waitcnt lgkmcnt(0)
	v_sub_f32_e32 v87, v86, v92
	v_add_f32_e32 v87, v87, v93
	v_mul_f32_e32 v87, 0x3fb8aa3b, v87
	v_exp_f32_e32 v87, v87
	s_nop 0
	v_mul_f32_e32 v78, v78, v87
	v_mul_f32_e32 v87, 0x3d800000, v78
.LBB0_440:
	s_or_b64 exec, exec, s[90:91]
	v_mov_b32_e32 v78, 0
	v_mov_b32_e32 v88, 0
	s_and_saveexec_b64 s[90:91], s[56:57]
	s_cbranch_execz .LBB0_442
	s_waitcnt lgkmcnt(0)
	v_sub_f32_e32 v86, v86, v94
	v_add_f32_e32 v86, v86, v95
	v_mul_f32_e32 v86, 0x3fb8aa3b, v86
	v_exp_f32_e32 v86, v86
	s_nop 0
	v_mul_f32_e32 v74, v74, v86
	v_mul_f32_e32 v88, 0x3d800000, v74
.LBB0_442:
	s_or_b64 exec, exec, s[90:91]
	v_cvt_pk_bf16_f32 v74, v87, s0
	ds_write_b16 v164, v74
	v_cvt_pk_bf16_f32 v74, v88, s0
	ds_write_b16 v164, v74 offset:32
	v_add_f32_e32 v74, v87, v88
	s_nop 1
	v_mov_b32_dpp v86, v74 quad_perm:[1,0,3,2] row_mask:0xf bank_mask:0xf
	ds_read_b32 v82, v82 offset:12
	s_waitcnt lgkmcnt(1)
	v_add_f32_e32 v74, v74, v86
	s_nop 1
	v_mov_b32_dpp v86, v74 quad_perm:[2,3,0,1] row_mask:0xf bank_mask:0xf
	s_waitcnt lgkmcnt(0)
	v_add_f32_e32 v74, v74, v86
	s_nop 1
	v_mov_b32_dpp v86, v74 row_half_mirror row_mask:0xf bank_mask:0xf
	s_waitcnt lgkmcnt(0)
	v_add_f32_e32 v74, v74, v86
	s_nop 1
	v_mov_b32_dpp v86, v74 row_mirror row_mask:0xf bank_mask:0xf
	s_and_saveexec_b64 s[90:91], s[58:59]
	s_cbranch_execz .LBB0_444
	s_waitcnt lgkmcnt(0)
	v_sub_f32_e32 v78, v82, v92
	v_add_f32_e32 v78, v78, v93
	v_mul_f32_e32 v78, 0x3fb8aa3b, v78
	v_exp_f32_e32 v78, v78
	s_nop 0
	v_mul_f32_e32 v78, v79, v78
	v_mul_f32_e32 v78, 0x3d800000, v78
.LBB0_444:
	s_or_b64 exec, exec, s[90:91]
	v_mov_b32_e32 v79, 0
	s_and_saveexec_b64 s[90:91], s[60:61]
	s_cbranch_execz .LBB0_446
	s_waitcnt lgkmcnt(0)
	v_sub_f32_e32 v79, v82, v94
	v_add_f32_e32 v79, v79, v95
	v_mul_f32_e32 v79, 0x3fb8aa3b, v79
	v_exp_f32_e32 v79, v79
	s_nop 0
	v_mul_f32_e32 v75, v75, v79
	v_mul_f32_e32 v79, 0x3d800000, v75
